# mixC epilogue: 16 serialised PO/norm_g loads issued up-front before the barrier, counted vmcnt waits
# speedup vs baseline: 1.0080x; 1.0058x over previous
; DI unsigned pack2(float a, float b) { const f32x2 v = {a, b}; return __builtin_bit_cast(unsigned, __builtin_convertvector(v, bf16v2)); }
; DI float bflo(unsigned w) { return __uint_as_float(w << 16); }
; DI float bfhi(unsigned w) { return __uint_as_float(w & 0xffff0000u); }
; DI void mlstmC_pair(const Params& p, char* lds_all, int pair) {
;     ...
;   __syncthreads();
; #pragma unroll
;   for (int tt = 0; tt < 2; ++tt) {
;     const int tq = tt * 32 + l31;
;     float t1 = 0.f, t2 = 0.f;
;     for (int e4 = 0; e4 < 4; ++e4) { t1 += red[(e4 * 64 + tq) * 2]; t2 += red[(e4 * 64 + tq) * 2 + 1]; }
;     const float mu = t1 * (1.f / 128.f);
;     const float var = fmaxf(t2 * (1.f / 128.f) - mu * mu, 0.f);
;     const float rstd = rsqrtf(var + LN_EPS);
;     const size_t row = (size_t)b * SEQ + c * 64 + tq;
; #pragma unroll
;     for (int g = 0; g < 4; ++g) {
;       const int e0 = et * 32 + 8 * g + 4 * hh;
;       const uint2 og = *(const uint2*)(PO + row * 512 + hd * 128 + e0);
;       const float4 gg = *(const float4*)(ng + e0);
;       const float o0 = __builtin_amdgcn_rcpf(1.f + __expf(-bflo(og.x))), o1 = __builtin_amdgcn_rcpf(1.f + __expf(-bfhi(og.x))), o2 = __builtin_amdgcn_rcpf(1.f + __expf(-bflo(og.y))), o3 = __builtin_amdgcn_rcpf(1.f + __expf(-bfhi(og.y)));
;       uint2 o;
;       o.x = pack2(o0 * (Hn[tt][4 * g] - mu) * rstd * gg.x, o1 * (Hn[tt][4 * g + 1] - mu) * rstd * gg.y);
;       o.y = pack2(o2 * (Hn[tt][4 * g + 2] - mu) * rstd * gg.z, o3 * (Hn[tt][4 * g + 3] - mu) * rstd * gg.w);
.LBB0_569:
	s_or_b64 exec, exec, s[4:5]
	v_or_b32_e32 v74, v22, v36
	v_or_b32_e32 v75, v37, v54
	v_mov_b32_e32 v185, v23
	v_mov_b32_e32 v187, v23
	v_or_b32_e32 v184, v74, v53
	v_or_b32_e32 v186, v74, v52
	v_lshlrev_b64 v[184:185], 10, v[184:185]
	v_lshlrev_b64 v[186:187], 10, v[186:187]
	v_lshlrev_b32_e32 v76, 1, v47
	v_mov_b32_e32 v77, 0
	v_lshlrev_b32_e32 v78, 1, v75
	v_mov_b32_e32 v79, 0
	v_lshl_add_u64 v[188:189], s[74:75], 0, v[76:77]
	v_lshl_add_u64 v[188:189], v[188:189], 0, v[78:79]
	v_lshl_add_u64 v[184:185], v[188:189], 0, v[184:185]
	v_lshl_add_u64 v[186:187], v[188:189], 0, v[186:187]
	v_lshlrev_b32_e32 v76, 2, v47
	v_lshlrev_b32_e32 v78, 2, v75
	v_lshl_add_u64 v[190:191], s[38:39], 0, v[76:77]
	v_lshl_add_u64 v[190:191], v[190:191], 0, v[78:79]
	global_load_dwordx2 v[224:225], v[184:185], off
	global_load_dwordx4 v[240:243], v[190:191], off
	global_load_dwordx2 v[226:227], v[184:185], off offset:16
	global_load_dwordx4 v[244:247], v[190:191], off offset:32
	global_load_dwordx2 v[228:229], v[184:185], off offset:32
	global_load_dwordx4 v[212:215], v[190:191], off offset:64
	global_load_dwordx2 v[230:231], v[184:185], off offset:48
	global_load_dwordx4 v[216:219], v[190:191], off offset:96
	global_load_dwordx2 v[232:233], v[186:187], off
	global_load_dwordx2 v[234:235], v[186:187], off offset:16
	global_load_dwordx2 v[236:237], v[186:187], off offset:32
	global_load_dwordx2 v[238:239], v[186:187], off offset:48
	s_waitcnt lgkmcnt(1)
	v_lshl_add_u32 v10, v53, 3, v51
	s_waitcnt lgkmcnt(0)
	s_barrier
	v_add_u32_e32 v14, 0xfe00, v10
	ds_read_b64 v[10:11], v10 offset:65024
	ds_read2st64_b64 v[56:59], v14 offset0:1 offset1:2
	ds_read_b64 v[14:15], v14 offset:1536
	v_lshlrev_b32_e32 v20, 2, v47
	v_or_b32_e32 v55, v22, v36
	s_waitcnt lgkmcnt(2)
	v_pk_add_f32 v[10:11], v[10:11], 0 op_sel_hi:[1,0]
	v_lshl_add_u64 v[4:5], s[38:39], 0, v[20:21]
	s_waitcnt lgkmcnt(1)
	v_pk_add_f32 v[10:11], v[10:11], v[56:57]
	v_lshlrev_b32_e32 v20, 1, v47
	v_pk_add_f32 v[10:11], v[10:11], v[58:59]
	v_or_b32_e32 v22, v55, v53
	s_waitcnt lgkmcnt(0)
	v_pk_add_f32 v[10:11], v[10:11], v[14:15]
	v_lshl_add_u64 v[12:13], s[74:75], 0, v[20:21]
	v_pk_mul_f32 v[14:15], v[10:11], s[78:79] op_sel_hi:[1,0]
	v_or_b32_e32 v37, v37, v54
	v_fma_f32 v10, -v14, v14, v15
	v_max_f32_e32 v10, 0, v10
	v_add_f32_e32 v10, 0x3727c5ac, v10
	v_cmp_gt_f32_e32 vcc, s22, v10
	v_mul_f32_e32 v11, 0x4b800000, v10
	v_lshlrev_b32_e32 v58, 2, v37
	v_cndmask_b32_e32 v10, v10, v11, vcc
	v_rsq_f32_e32 v10, v10
	v_mov_b32_e32 v59, v21
	v_lshl_add_u64 v[4:5], v[4:5], 0, v[58:59]
	v_pk_add_f32 v[42:43], v[42:43], v[14:15] op_sel_hi:[1,0] neg_lo:[0,1] neg_hi:[0,1]
	v_mul_f32_e32 v11, 0x45800000, v10
	v_cndmask_b32_e32 v36, v10, v11, vcc
	v_lshlrev_b64 v[10:11], 10, v[22:23]
	v_lshl_add_u64 v[46:47], v[12:13], 0, v[10:11]
	v_lshlrev_b64 v[10:11], 11, v[22:23]
	v_lshl_add_u64 v[10:11], s[68:69], 0, v[10:11]
	v_lshl_add_u64 v[60:61], v[10:11], 0, v[20:21]
	v_lshlrev_b32_e32 v10, 1, v37
	v_mov_b32_e32 v11, v21
	v_lshl_add_u64 v[46:47], v[46:47], 0, v[10:11]
	v_pk_add_f32 v[38:39], v[38:39], v[14:15] op_sel_hi:[1,0] neg_lo:[0,1] neg_hi:[0,1]
	v_pk_add_f32 v[40:41], v[40:41], v[14:15] op_sel_hi:[1,0] neg_lo:[0,1] neg_hi:[0,1]
	v_pk_add_f32 v[32:33], v[32:33], v[14:15] op_sel_hi:[1,0] neg_lo:[0,1] neg_hi:[0,1]
	v_pk_add_f32 v[34:35], v[34:35], v[14:15] op_sel_hi:[1,0] neg_lo:[0,1] neg_hi:[0,1]
	v_pk_add_f32 v[24:25], v[24:25], v[14:15] op_sel_hi:[1,0] neg_lo:[0,1] neg_hi:[0,1]
	s_add_i32 s27, s27, s70
	s_add_i32 s26, s26, s17
	s_add_i32 s16, s16, s17
	s_cmpk_lt_i32 s27, 0x800
	s_waitcnt vmcnt(11)
	v_lshlrev_b32_e32 v22, 16, v224
	v_mul_f32_e32 v22, 0xbfb8aa3b, v22
	v_exp_f32_e32 v22, v22
	s_nop 0
	v_add_f32_e32 v22, 1.0, v22
	v_rcp_f32_e32 v62, v22
	v_and_b32_e32 v22, 0xffff0000, v224
	v_mul_f32_e32 v22, 0xbfb8aa3b, v22
	v_exp_f32_e32 v22, v22
	s_nop 0
	v_add_f32_e32 v22, 1.0, v22
	v_rcp_f32_e32 v63, v22
	v_lshlrev_b32_e32 v22, 16, v225
	v_mul_f32_e32 v22, 0xbfb8aa3b, v22
	v_exp_f32_e32 v22, v22
	v_pk_mul_f32 v[42:43], v[42:43], v[62:63]
	v_add_f32_e32 v22, 1.0, v22
	v_rcp_f32_e32 v64, v22
	v_and_b32_e32 v22, 0xffff0000, v225
	v_mul_f32_e32 v22, 0xbfb8aa3b, v22
	v_exp_f32_e32 v22, v22
	v_pk_mul_f32 v[42:43], v[42:43], v[36:37] op_sel_hi:[1,0]
	v_add_f32_e32 v22, 1.0, v22
	v_rcp_f32_e32 v65, v22
	s_waitcnt vmcnt(10)
	v_pk_mul_f32 v[42:43], v[240:241], v[42:43]
	s_nop 0
	v_cvt_pk_bf16_f32 v56, v42, v43
	v_pk_add_f32 v[42:43], v[44:45], v[14:15] op_sel_hi:[1,0] neg_lo:[0,1] neg_hi:[0,1]
	v_lshl_add_u64 v[44:45], v[60:61], 0, v[10:11]
	v_pk_mul_f32 v[42:43], v[42:43], v[64:65]
	v_pk_add_f32 v[14:15], v[26:27], v[14:15] op_sel_hi:[1,0] neg_lo:[0,1] neg_hi:[0,1]
	v_pk_mul_f32 v[42:43], v[42:43], v[36:37] op_sel_hi:[1,0]
	s_nop 0
	v_pk_mul_f32 v[42:43], v[242:243], v[42:43]
	s_nop 0
	v_cvt_pk_bf16_f32 v57, v42, v43
	v_lshl_add_u64 v[42:43], v[44:45], 0, s[80:81]
	v_add_co_u32_e32 v44, vcc, s23, v44
	s_nop 1
	v_addc_co_u32_e32 v45, vcc, 0, v45, vcc
	global_store_dwordx2 v[44:45], v[56:57], off offset:1024
	s_waitcnt vmcnt(10)
	v_lshlrev_b32_e32 v22, 16, v226
	v_mul_f32_e32 v22, 0xbfb8aa3b, v22
	v_exp_f32_e32 v22, v22
	s_nop 0
	v_add_f32_e32 v22, 1.0, v22
	v_rcp_f32_e32 v60, v22
	v_and_b32_e32 v22, 0xffff0000, v226
	v_mul_f32_e32 v22, 0xbfb8aa3b, v22
	v_exp_f32_e32 v22, v22
	s_nop 0
	v_add_f32_e32 v22, 1.0, v22
	v_rcp_f32_e32 v61, v22
	v_lshlrev_b32_e32 v22, 16, v227
	v_mul_f32_e32 v22, 0xbfb8aa3b, v22
	v_exp_f32_e32 v22, v22
	v_pk_mul_f32 v[38:39], v[38:39], v[60:61]
	v_add_f32_e32 v22, 1.0, v22
	v_rcp_f32_e32 v44, v22
	v_and_b32_e32 v22, 0xffff0000, v227
	v_mul_f32_e32 v22, 0xbfb8aa3b, v22
	v_exp_f32_e32 v22, v22
	v_pk_mul_f32 v[38:39], v[36:37], v[38:39] op_sel_hi:[0,1]
	v_add_f32_e32 v22, 1.0, v22
	v_rcp_f32_e32 v45, v22
	s_waitcnt vmcnt(9)
; DI unsigned pack2(float a, float b) { const f32x2 v = {a, b}; return __builtin_bit_cast(unsigned, __builtin_convertvector(v, bf16v2)); }
; DI float bflo(unsigned w) { return __uint_as_float(w << 16); }
; DI float bfhi(unsigned w) { return __uint_as_float(w & 0xffff0000u); }
; DI void mlstmC_pair(const Params& p, char* lds_all, int pair) {
;     ...
;   for (int tt = 0; tt < 2; ++tt) {
;     const int tq = tt * 32 + l31;
;     float t1 = 0.f, t2 = 0.f;
;     for (int e4 = 0; e4 < 4; ++e4) { t1 += red[(e4 * 64 + tq) * 2]; t2 += red[(e4 * 64 + tq) * 2 + 1]; }
;     const float mu = t1 * (1.f / 128.f);
;     const float var = fmaxf(t2 * (1.f / 128.f) - mu * mu, 0.f);
;     const float rstd = rsqrtf(var + LN_EPS);
;     const size_t row = (size_t)b * SEQ + c * 64 + tq;
; #pragma unroll
;     for (int g = 0; g < 4; ++g) {
;       const int e0 = et * 32 + 8 * g + 4 * hh;
;       const uint2 og = *(const uint2*)(PO + row * 512 + hd * 128 + e0);
;       const float4 gg = *(const float4*)(ng + e0);
;       const float o0 = __builtin_amdgcn_rcpf(1.f + __expf(-bflo(og.x))), o1 = __builtin_amdgcn_rcpf(1.f + __expf(-bfhi(og.x))), o2 = __builtin_amdgcn_rcpf(1.f + __expf(-bflo(og.y))), o3 = __builtin_amdgcn_rcpf(1.f + __expf(-bfhi(og.y)));
;       uint2 o;
;       o.x = pack2(o0 * (Hn[tt][4 * g] - mu) * rstd * gg.x, o1 * (Hn[tt][4 * g + 1] - mu) * rstd * gg.y);
;       o.y = pack2(o2 * (Hn[tt][4 * g + 2] - mu) * rstd * gg.z, o3 * (Hn[tt][4 * g + 3] - mu) * rstd * gg.w);
;       *(uint2*)(MIX + row * 1024 + 512 + hd * 128 + e0) = o;
;     }
;   }
	v_pk_mul_f32 v[38:39], v[244:245], v[38:39]
	v_pk_mul_f32 v[40:41], v[40:41], v[44:45]
	v_cvt_pk_bf16_f32 v38, v38, v39
	v_pk_mul_f32 v[40:41], v[36:37], v[40:41] op_sel_hi:[0,1]
	v_pk_mul_f32 v[40:41], v[246:247], v[40:41]
	s_nop 0
	v_cvt_pk_bf16_f32 v39, v40, v41
	global_store_dwordx2 v[42:43], v[38:39], off offset:16
	s_waitcnt vmcnt(9)
	v_lshlrev_b32_e32 v22, 16, v228
	v_mul_f32_e32 v22, 0xbfb8aa3b, v22
	v_exp_f32_e32 v22, v22
	s_nop 0
	v_add_f32_e32 v22, 1.0, v22
	v_rcp_f32_e32 v44, v22
	v_and_b32_e32 v22, 0xffff0000, v228
	v_mul_f32_e32 v22, 0xbfb8aa3b, v22
	v_exp_f32_e32 v22, v22
	s_nop 0
	v_add_f32_e32 v22, 1.0, v22
	v_rcp_f32_e32 v45, v22
	v_lshlrev_b32_e32 v22, 16, v229
	v_mul_f32_e32 v22, 0xbfb8aa3b, v22
	v_exp_f32_e32 v22, v22
	v_pk_mul_f32 v[32:33], v[32:33], v[44:45]
	v_add_f32_e32 v22, 1.0, v22
	v_rcp_f32_e32 v56, v22
	v_and_b32_e32 v22, 0xffff0000, v229
	v_mul_f32_e32 v22, 0xbfb8aa3b, v22
	v_exp_f32_e32 v22, v22
	v_pk_mul_f32 v[32:33], v[36:37], v[32:33] op_sel_hi:[0,1]
	v_add_f32_e32 v22, 1.0, v22
	v_rcp_f32_e32 v57, v22
	s_waitcnt vmcnt(8)
	v_pk_mul_f32 v[32:33], v[212:213], v[32:33]
	v_pk_mul_f32 v[34:35], v[34:35], v[56:57]
	v_cvt_pk_bf16_f32 v32, v32, v33
	v_pk_mul_f32 v[34:35], v[36:37], v[34:35] op_sel_hi:[0,1]
	v_pk_mul_f32 v[34:35], v[214:215], v[34:35]
	s_nop 0
	v_cvt_pk_bf16_f32 v33, v34, v35
	s_waitcnt vmcnt(7)
	v_lshlrev_b32_e32 v22, 16, v230
	global_store_dwordx2 v[42:43], v[32:33], off offset:32
	v_mul_f32_e32 v22, 0xbfb8aa3b, v22
	v_exp_f32_e32 v22, v22
	s_nop 0
	v_add_f32_e32 v22, 1.0, v22
	v_rcp_f32_e32 v32, v22
	v_and_b32_e32 v22, 0xffff0000, v230
	v_mul_f32_e32 v22, 0xbfb8aa3b, v22
	v_exp_f32_e32 v22, v22
	s_nop 0
	v_add_f32_e32 v22, 1.0, v22
	v_rcp_f32_e32 v33, v22
	v_lshlrev_b32_e32 v22, 16, v231
	v_mul_f32_e32 v22, 0xbfb8aa3b, v22
	v_exp_f32_e32 v22, v22
	v_pk_mul_f32 v[24:25], v[24:25], v[32:33]
	v_add_f32_e32 v22, 1.0, v22
	v_rcp_f32_e32 v34, v22
	v_and_b32_e32 v22, 0xffff0000, v231
	v_mul_f32_e32 v22, 0xbfb8aa3b, v22
	v_exp_f32_e32 v22, v22
	v_pk_mul_f32 v[24:25], v[36:37], v[24:25] op_sel_hi:[0,1]
	v_add_f32_e32 v22, 1.0, v22
	v_rcp_f32_e32 v35, v22
	s_waitcnt vmcnt(7)
	v_pk_mul_f32 v[24:25], v[216:217], v[24:25]
	v_pk_mul_f32 v[14:15], v[14:15], v[34:35]
	v_cvt_pk_bf16_f32 v24, v24, v25
	v_pk_mul_f32 v[14:15], v[36:37], v[14:15] op_sel_hi:[0,1]
	v_pk_mul_f32 v[14:15], v[218:219], v[14:15]
	s_nop 0
	v_cvt_pk_bf16_f32 v25, v14, v15
	v_lshl_add_u32 v14, v52, 3, v51
	v_add_u32_e32 v22, 0xfe00, v14
	ds_read_b64 v[14:15], v14 offset:65024
	global_store_dwordx2 v[42:43], v[24:25], off offset:48
	ds_read2st64_b64 v[24:27], v22 offset0:1 offset1:2
	s_waitcnt lgkmcnt(1)
	v_pk_add_f32 v[14:15], v[14:15], 0 op_sel_hi:[1,0]
	s_waitcnt lgkmcnt(0)
	v_pk_add_f32 v[14:15], v[14:15], v[24:25]
	ds_read_b64 v[24:25], v22 offset:1536
	v_pk_add_f32 v[14:15], v[14:15], v[26:27]
	s_waitcnt lgkmcnt(0)
	v_pk_add_f32 v[14:15], v[14:15], v[24:25]
	s_nop 0
	v_pk_mul_f32 v[14:15], v[14:15], s[78:79] op_sel_hi:[1,0]
	s_nop 0
	v_fma_f32 v22, -v14, v14, v15
	v_max_f32_e32 v22, 0, v22
	v_add_f32_e32 v22, 0x3727c5ac, v22
	v_cmp_gt_f32_e32 vcc, s22, v22
	v_mul_f32_e32 v24, 0x4b800000, v22
	v_pk_add_f32 v[28:29], v[28:29], v[14:15] op_sel_hi:[1,0] neg_lo:[0,1] neg_hi:[0,1]
	v_cndmask_b32_e32 v22, v22, v24, vcc
	v_rsq_f32_e32 v22, v22
	v_pk_add_f32 v[30:31], v[30:31], v[14:15] op_sel_hi:[1,0] neg_lo:[0,1] neg_hi:[0,1]
	v_pk_add_f32 v[16:17], v[16:17], v[14:15] op_sel_hi:[1,0] neg_lo:[0,1] neg_hi:[0,1]
	v_pk_add_f32 v[18:19], v[18:19], v[14:15] op_sel_hi:[1,0] neg_lo:[0,1] neg_hi:[0,1]
	v_mul_f32_e32 v24, 0x45800000, v22
	v_cndmask_b32_e32 v24, v22, v24, vcc
	v_or_b32_e32 v22, v55, v52
	v_lshlrev_b64 v[26:27], 10, v[22:23]
	v_lshl_add_u64 v[12:13], v[12:13], 0, v[26:27]
	v_lshl_add_u64 v[12:13], v[12:13], 0, v[10:11]
	v_lshlrev_b64 v[22:23], 11, v[22:23]
	v_lshl_add_u64 v[22:23], s[68:69], 0, v[22:23]
	v_lshl_add_u64 v[22:23], v[22:23], 0, v[20:21]
	v_lshl_add_u64 v[22:23], v[22:23], 0, v[10:11]
	v_lshl_add_u64 v[10:11], v[22:23], 0, s[80:81]
	v_add_co_u32_e32 v22, vcc, s23, v22
	v_pk_add_f32 v[6:7], v[6:7], v[14:15] op_sel_hi:[1,0] neg_lo:[0,1] neg_hi:[0,1]
	s_nop 0
	v_addc_co_u32_e32 v23, vcc, 0, v23, vcc
	v_pk_add_f32 v[8:9], v[8:9], v[14:15] op_sel_hi:[1,0] neg_lo:[0,1] neg_hi:[0,1]
	v_pk_add_f32 v[0:1], v[0:1], v[14:15] op_sel_hi:[1,0] neg_lo:[0,1] neg_hi:[0,1]
	v_pk_add_f32 v[2:3], v[2:3], v[14:15] op_sel_hi:[1,0] neg_lo:[0,1] neg_hi:[0,1]
	s_waitcnt vmcnt(7)
; DI unsigned pack2(float a, float b) { const f32x2 v = {a, b}; return __builtin_bit_cast(unsigned, __builtin_convertvector(v, bf16v2)); }
; DI float bflo(unsigned w) { return __uint_as_float(w << 16); }
; DI float bfhi(unsigned w) { return __uint_as_float(w & 0xffff0000u); }
; DI void mlstmC_pair(const Params& p, char* lds_all, int pair) {
;     ...
;     for (int g = 0; g < 4; ++g) {
;       const int e0 = et * 32 + 8 * g + 4 * hh;
;       const uint2 og = *(const uint2*)(PO + row * 512 + hd * 128 + e0);
;       const float4 gg = *(const float4*)(ng + e0);
;       const float o0 = __builtin_amdgcn_rcpf(1.f + __expf(-bflo(og.x))), o1 = __builtin_amdgcn_rcpf(1.f + __expf(-bfhi(og.x))), o2 = __builtin_amdgcn_rcpf(1.f + __expf(-bflo(og.y))), o3 = __builtin_amdgcn_rcpf(1.f + __expf(-bfhi(og.y)));
;       uint2 o;
;       o.x = pack2(o0 * (Hn[tt][4 * g] - mu) * rstd * gg.x, o1 * (Hn[tt][4 * g + 1] - mu) * rstd * gg.y);
;       o.y = pack2(o2 * (Hn[tt][4 * g + 2] - mu) * rstd * gg.z, o3 * (Hn[tt][4 * g + 3] - mu) * rstd * gg.w);
;       *(uint2*)(MIX + row * 1024 + 512 + hd * 128 + e0) = o;
;     }
;   }
;   __syncthreads();
	v_lshlrev_b32_e32 v20, 16, v232
	v_mul_f32_e32 v20, 0xbfb8aa3b, v20
	v_exp_f32_e32 v20, v20
	s_nop 0
	v_add_f32_e32 v20, 1.0, v20
	v_rcp_f32_e32 v36, v20
	v_and_b32_e32 v20, 0xffff0000, v232
	v_mul_f32_e32 v20, 0xbfb8aa3b, v20
	v_exp_f32_e32 v20, v20
	s_nop 0
	v_add_f32_e32 v20, 1.0, v20
	v_rcp_f32_e32 v37, v20
	v_lshlrev_b32_e32 v20, 16, v233
	v_mul_f32_e32 v20, 0xbfb8aa3b, v20
	v_exp_f32_e32 v20, v20
	v_pk_mul_f32 v[28:29], v[28:29], v[36:37]
	v_add_f32_e32 v20, 1.0, v20
	v_rcp_f32_e32 v26, v20
	v_and_b32_e32 v20, 0xffff0000, v233
	v_mul_f32_e32 v20, 0xbfb8aa3b, v20
	v_exp_f32_e32 v20, v20
	v_pk_mul_f32 v[28:29], v[28:29], v[24:25] op_sel_hi:[1,0]
	v_add_f32_e32 v20, 1.0, v20
	v_rcp_f32_e32 v27, v20
	v_pk_mul_f32 v[28:29], v[240:241], v[28:29]
	v_pk_mul_f32 v[26:27], v[30:31], v[26:27]
	s_nop 0
	v_pk_mul_f32 v[26:27], v[26:27], v[24:25] op_sel_hi:[1,0]
	v_cvt_pk_bf16_f32 v28, v28, v29
	v_pk_mul_f32 v[26:27], v[242:243], v[26:27]
	s_nop 0
	v_cvt_pk_bf16_f32 v29, v26, v27
	global_store_dwordx2 v[22:23], v[28:29], off offset:1024
	s_waitcnt vmcnt(7)
	v_lshlrev_b32_e32 v20, 16, v234
	v_mul_f32_e32 v20, 0xbfb8aa3b, v20
	v_exp_f32_e32 v20, v20
	s_nop 0
	v_add_f32_e32 v20, 1.0, v20
	v_rcp_f32_e32 v30, v20
	v_and_b32_e32 v20, 0xffff0000, v234
	v_mul_f32_e32 v20, 0xbfb8aa3b, v20
	v_exp_f32_e32 v20, v20
	s_nop 0
	v_add_f32_e32 v20, 1.0, v20
	v_rcp_f32_e32 v31, v20
	v_lshlrev_b32_e32 v20, 16, v235
	v_mul_f32_e32 v20, 0xbfb8aa3b, v20
	v_exp_f32_e32 v20, v20
	v_pk_mul_f32 v[16:17], v[16:17], v[30:31]
	v_add_f32_e32 v20, 1.0, v20
	v_rcp_f32_e32 v22, v20
	v_and_b32_e32 v20, 0xffff0000, v235
	v_mul_f32_e32 v20, 0xbfb8aa3b, v20
	v_exp_f32_e32 v20, v20
	v_pk_mul_f32 v[16:17], v[24:25], v[16:17] op_sel_hi:[0,1]
	v_add_f32_e32 v20, 1.0, v20
	v_rcp_f32_e32 v23, v20
	v_pk_mul_f32 v[16:17], v[244:245], v[16:17]
	v_pk_mul_f32 v[18:19], v[18:19], v[22:23]
	v_cvt_pk_bf16_f32 v16, v16, v17
	v_pk_mul_f32 v[18:19], v[24:25], v[18:19] op_sel_hi:[0,1]
	v_pk_mul_f32 v[18:19], v[246:247], v[18:19]
	s_nop 0
	v_cvt_pk_bf16_f32 v17, v18, v19
	global_store_dwordx2 v[10:11], v[16:17], off offset:16
	s_waitcnt vmcnt(7)
	v_lshlrev_b32_e32 v18, 16, v236
	v_and_b32_e32 v16, 0xffff0000, v236
	v_mul_f32_e32 v16, 0xbfb8aa3b, v16
	v_exp_f32_e32 v16, v16
	v_mul_f32_e32 v18, 0xbfb8aa3b, v18
	v_exp_f32_e32 v18, v18
	v_add_f32_e32 v16, 1.0, v16
	v_rcp_f32_e32 v23, v16
	v_lshlrev_b32_e32 v16, 16, v237
	v_mul_f32_e32 v16, 0xbfb8aa3b, v16
	v_exp_f32_e32 v16, v16
	v_add_f32_e32 v18, 1.0, v18
	v_rcp_f32_e32 v22, v18
	v_add_f32_e32 v16, 1.0, v16
	v_rcp_f32_e32 v26, v16
	v_and_b32_e32 v16, 0xffff0000, v237
	v_mul_f32_e32 v16, 0xbfb8aa3b, v16
	v_exp_f32_e32 v16, v16
	v_pk_mul_f32 v[6:7], v[6:7], v[22:23]
	v_add_f32_e32 v16, 1.0, v16
	v_rcp_f32_e32 v27, v16
	v_pk_mul_f32 v[6:7], v[24:25], v[6:7] op_sel_hi:[0,1]
	v_pk_mul_f32 v[8:9], v[8:9], v[26:27]
	s_nop 0
	v_pk_mul_f32 v[8:9], v[24:25], v[8:9] op_sel_hi:[0,1]
	v_pk_mul_f32 v[6:7], v[212:213], v[6:7]
	v_pk_mul_f32 v[8:9], v[214:215], v[8:9]
	v_cvt_pk_bf16_f32 v6, v6, v7
	v_cvt_pk_bf16_f32 v7, v8, v9
	s_nop 0
	global_store_dwordx2 v[10:11], v[6:7], off offset:32
	s_waitcnt vmcnt(7)
	v_lshlrev_b32_e32 v6, 16, v238
	v_and_b32_e32 v7, 0xffff0000, v238
	v_lshlrev_b32_e32 v8, 16, v239
	v_and_b32_e32 v9, 0xffff0000, v239
	v_mul_f32_e32 v6, 0xbfb8aa3b, v6
	v_mul_f32_e32 v7, 0xbfb8aa3b, v7
	v_mul_f32_e32 v8, 0xbfb8aa3b, v8
	v_mul_f32_e32 v9, 0xbfb8aa3b, v9
	v_exp_f32_e32 v6, v6
	v_exp_f32_e32 v7, v7
	v_exp_f32_e32 v8, v8
	v_exp_f32_e32 v9, v9
	v_add_f32_e32 v6, 1.0, v6
	v_add_f32_e32 v7, 1.0, v7
	v_add_f32_e32 v8, 1.0, v8
	v_add_f32_e32 v9, 1.0, v9
	v_rcp_f32_e32 v6, v6
	v_rcp_f32_e32 v7, v7
	v_rcp_f32_e32 v8, v8
	v_rcp_f32_e32 v9, v9
	v_pk_mul_f32 v[0:1], v[0:1], v[6:7]
	s_nop 0
	v_pk_mul_f32 v[0:1], v[24:25], v[0:1] op_sel_hi:[0,1]
	v_pk_mul_f32 v[2:3], v[2:3], v[8:9]
	v_pk_mul_f32 v[0:1], v[216:217], v[0:1]
	v_pk_mul_f32 v[2:3], v[24:25], v[2:3] op_sel_hi:[0,1]
	v_pk_mul_f32 v[2:3], v[218:219], v[2:3]
	v_cvt_pk_bf16_f32 v0, v0, v1
	v_cvt_pk_bf16_f32 v1, v2, v3
	global_store_dwordx2 v[10:11], v[0:1], off offset:48
	s_barrier
	s_cbranch_scc0 .LBB0_626
